# P0 x to f16 row conversion loop software-pipelined: next iteration loads issued before the current compute and stores
# speedup vs baseline: 1.0029x; 1.0014x over previous
; __device__ __forceinline__ unsigned pk2(float lo, float hi) { f32x2 v = {lo, hi}; h16x2 b = __builtin_convertvector(v, h16x2); return __builtin_bit_cast(unsigned, b); }
; __device__ __forceinline__ void p0_prologue(const Ctx& F, const float* x, const float* g1, const float* gmix, const float* g2, const float* wg1, const float* wu1, const float* wd1, const float* win, const float* wout, const float* wg2, const float* wu2, const float* wd2, const float* dw2, const floa ...
;     ...
;     for (int m = F.gw * 2; m < M; m += F.NGW * 2) {
;         f32x4 v[2][4]; float sq[2] = {0.f, 0.f};
; #pragma unroll
;         for (int u = 0; u < 2; ++u) { const f32x4* xr = (const f32x4*)(x + (size_t)(m + u) * D) + F.lane;
; #pragma unroll
;             for (int j = 0; j < 4; ++j) { v[u][j] = xr[64 * j]; sq[u] += (v[u][j].x * v[u][j].x + v[u][j].y * v[u][j].y) + (v[u][j].z * v[u][j].z + v[u][j].w * v[u][j].w); } }
; #pragma unroll
;         for (int u = 0; u < 2; ++u) { u32x2* o8 = (u32x2*)(XB + (size_t)(m + u) * D) + F.lane;
; #pragma unroll
;             for (int j = 0; j < 4; ++j) { u32x2 o; o.x = pk2(v[u][j].x, v[u][j].y); o.y = pk2(v[u][j].z, v[u][j].w); o8[64 * j] = o; }
;             const float rstd = rsqrtf(wave_sum_d(sq[u]) * (1.f / D) + NORM_EPS); if (F.lane == 0) RS0[m + u] = rstd; }
;     }
.LBB0_85:
	s_or_b64 exec, exec, s[16:17]
	s_add_i32 s2, s2, s6
	s_add_u32 s8, s8, s10
	s_addc_u32 s9, s9, s11
	v_lshl_add_u64 v[18:19], v[18:19], 0, s[12:13]
	s_cmp_lt_i32 s2, 0x8000
	s_cbranch_scc0 .LBB0_90
	s_waitcnt vmcnt(10)
	s_branch .Lxc_body
.LBB0_86:
	global_load_dwordx4 v[26:29], v[20:21], off offset:-4096
	global_load_dwordx4 v[30:33], v[20:21], off offset:-3072
	global_load_dwordx4 v[34:37], v[20:21], off offset:-2048
	global_load_dwordx4 v[38:41], v[20:21], off offset:-1024
	global_load_dwordx4 v[14:17], v[20:21], off
	global_load_dwordx4 v[10:13], v[20:21], off offset:1024
	global_load_dwordx4 v[6:9], v[20:21], off offset:2048
	global_load_dwordx4 v[2:5], v[20:21], off offset:3072
	s_waitcnt vmcnt(0)
.Lxc_body:
	v_mov_b64_e32 v[114:115], v[2:3]
	v_mov_b64_e32 v[116:117], v[4:5]
	v_mov_b64_e32 v[118:119], v[6:7]
	v_mov_b64_e32 v[120:121], v[8:9]
	v_mov_b64_e32 v[122:123], v[10:11]
	v_mov_b64_e32 v[124:125], v[12:13]
	v_mov_b64_e32 v[126:127], v[14:15]
	v_mov_b64_e32 v[128:129], v[16:17]
	v_mov_b64_e32 v[138:139], v[26:27]
	v_mov_b64_e32 v[140:141], v[28:29]
	v_mov_b64_e32 v[142:143], v[30:31]
	v_mov_b64_e32 v[144:145], v[32:33]
	v_mov_b64_e32 v[146:147], v[34:35]
	v_mov_b64_e32 v[148:149], v[36:37]
	v_mov_b64_e32 v[150:151], v[38:39]
	v_mov_b64_e32 v[152:153], v[40:41]
	s_add_i32 s0, s2, s6
	s_cmp_lt_i32 s0, 0x8000
	s_cbranch_scc0 .Lxc_nopf
	v_lshl_add_u64 v[20:21], v[20:21], 0, s[14:15]
	global_load_dwordx4 v[26:29], v[20:21], off offset:-4096
	global_load_dwordx4 v[30:33], v[20:21], off offset:-3072
	global_load_dwordx4 v[34:37], v[20:21], off offset:-2048
	global_load_dwordx4 v[38:41], v[20:21], off offset:-1024
	global_load_dwordx4 v[14:17], v[20:21], off
	global_load_dwordx4 v[10:13], v[20:21], off offset:1024
	global_load_dwordx4 v[6:9], v[20:21], off offset:2048
	global_load_dwordx4 v[2:5], v[20:21], off offset:3072
.Lxc_nopf:
	v_mov_b32_e32 v50, 0
	v_lshl_add_u64 v[22:23], s[72:73], 0, v[18:19]
	v_add_co_u32_e64 v22, s[0:1], s3, v22
	v_mul_f32_e32 v51, v139, v139
	v_mul_f32_e32 v52, v141, v141
	v_mul_f32_e32 v53, v143, v143
	v_mul_f32_e32 v54, v145, v145
	v_mul_f32_e32 v55, v147, v147
	v_mul_f32_e32 v56, v149, v149
	v_fmac_f32_e32 v51, v138, v138
	v_fmac_f32_e32 v52, v140, v140
	v_fmac_f32_e32 v53, v142, v142
	v_fmac_f32_e32 v54, v144, v144
	v_mul_f32_e32 v57, v151, v151
	v_mul_f32_e32 v58, v153, v153
	v_cvt_pk_f16_f32 v42, v138, v139
	v_fmac_f32_e32 v55, v146, v146
	v_fmac_f32_e32 v56, v148, v148
	v_add_f32_e32 v138, v51, v52
	v_add_f32_e32 v139, v53, v54
	v_cvt_pk_f16_f32 v43, v140, v141
	v_fmac_f32_e32 v57, v150, v150
	v_fmac_f32_e32 v58, v152, v152
	v_add_f32_e32 v140, v55, v56
	v_add_f32_e32 v138, v138, v139
	v_add_f32_e32 v141, v57, v58
	v_add_f32_e32 v138, v138, v140
	v_add_f32_e32 v138, v138, v141
	v_mov_b32_e32 v139, 0
	v_addc_co_u32_e64 v23, s[0:1], 0, v23, s[0:1]
	v_add_f32_dpp v138, v138, v138 quad_perm:[1,0,3,2] row_mask:0xf bank_mask:0xf bound_ctrl:1
	v_cvt_pk_f16_f32 v44, v142, v143
	v_cvt_pk_f16_f32 v45, v144, v145
	v_add_f32_dpp v138, v138, v138 quad_perm:[2,3,0,1] row_mask:0xf bank_mask:0xf bound_ctrl:1
	v_cvt_pk_f16_f32 v46, v146, v147
	v_cvt_pk_f16_f32 v47, v148, v149
	v_add_f32_dpp v138, v138, v138 row_half_mirror row_mask:0xf bank_mask:0xf bound_ctrl:1
	v_cvt_pk_f16_f32 v48, v150, v151
	v_cvt_pk_f16_f32 v49, v152, v153
	v_add_f32_dpp v138, v138, v138 row_mirror row_mask:0xf bank_mask:0xf bound_ctrl:1
	global_store_dwordx2 v[22:23], v[42:43], off
	global_store_dwordx2 v[22:23], v[44:45], off offset:512
	global_store_dwordx2 v[22:23], v[46:47], off offset:1024
	global_store_dwordx2 v[22:23], v[48:49], off offset:1536
	v_mov_b32_dpp v50, v138 row_bcast:15 row_mask:0xa bank_mask:0xf
	v_add_f32_e32 v138, v138, v50
	s_nop 1
	v_mov_b32_dpp v139, v138 row_bcast:31 row_mask:0xc bank_mask:0xf
	v_add_f32_e32 v138, v138, v139
	s_nop 0
	v_readlane_b32 s0, v138, 63
	s_and_saveexec_b64 s[16:17], vcc
	s_cbranch_execz .LBB0_88
	v_fma_f32 v138, s0, v25, v1
	v_mul_f32_e32 v139, 0x4b800000, v138
	v_cmp_gt_f32_e64 s[0:1], s7, v138
	s_add_u32 s18, s72, s8
	s_addc_u32 s19, s73, s9
	v_cndmask_b32_e64 v138, v138, v139, s[0:1]
	v_rsq_f32_e32 v138, v138
	s_nop 0
	v_mul_f32_e32 v139, 0x45800000, v138
	v_cndmask_b32_e64 v138, v138, v139, s[0:1]
	global_store_dword v24, v138, s[18:19]
.LBB0_88:
	s_or_b64 exec, exec, s[16:17]
	v_mul_f32_e32 v138, v127, v127
	v_mul_f32_e32 v139, v129, v129
	v_fmac_f32_e32 v138, v126, v126
	v_fmac_f32_e32 v139, v128, v128
	v_add_f32_e32 v138, v138, v139
	v_mul_f32_e32 v139, v123, v123
	v_mul_f32_e32 v140, v125, v125
	v_fmac_f32_e32 v139, v122, v122
	v_fmac_f32_e32 v140, v124, v124
	v_add_f32_e32 v139, v139, v140
	v_add_f32_e32 v138, v138, v139
	v_mul_f32_e32 v139, v119, v119
	v_mul_f32_e32 v140, v121, v121
	v_fmac_f32_e32 v139, v118, v118
	v_fmac_f32_e32 v140, v120, v120
	v_add_f32_e32 v139, v139, v140
	v_add_f32_e32 v138, v138, v139
	v_mul_f32_e32 v139, v115, v115
	v_mul_f32_e32 v140, v117, v117
	v_fmac_f32_e32 v139, v114, v114
	v_fmac_f32_e32 v140, v116, v116
	v_add_f32_e32 v139, v139, v140
	v_add_f32_e32 v138, v138, v139
	v_cvt_pk_f16_f32 v114, v114, v115
	v_cvt_pk_f16_f32 v115, v116, v117
	global_store_dwordx2 v[22:23], v[114:115], off offset:3584
	v_add_f32_dpp v114, v138, v138 quad_perm:[1,0,3,2] row_mask:0xf bank_mask:0xf bound_ctrl:1
	v_mov_b32_e32 v115, 0
	v_cvt_pk_f16_f32 v126, v126, v127
	v_add_f32_dpp v114, v114, v114 quad_perm:[2,3,0,1] row_mask:0xf bank_mask:0xf bound_ctrl:1
	v_cvt_pk_f16_f32 v127, v128, v129
	v_cvt_pk_f16_f32 v122, v122, v123
	v_add_f32_dpp v114, v114, v114 row_half_mirror row_mask:0xf bank_mask:0xf bound_ctrl:1
	v_cvt_pk_f16_f32 v123, v124, v125
	v_cvt_pk_f16_f32 v118, v118, v119
	v_add_f32_dpp v114, v114, v114 row_mirror row_mask:0xf bank_mask:0xf bound_ctrl:1
	v_cvt_pk_f16_f32 v119, v120, v121
	global_store_dwordx2 v[22:23], v[126:127], off offset:2048
	v_mov_b32_dpp v115, v114 row_bcast:15 row_mask:0xa bank_mask:0xf
	v_add_f32_e32 v114, v114, v115
	v_mov_b32_e32 v115, 0
	global_store_dwordx2 v[22:23], v[122:123], off offset:2560
	global_store_dwordx2 v[22:23], v[118:119], off offset:3072
	v_mov_b32_dpp v115, v114 row_bcast:31 row_mask:0xc bank_mask:0xf
	v_add_f32_e32 v114, v114, v115
	s_nop 0
	v_readlane_b32 s0, v114, 63
	s_and_saveexec_b64 s[16:17], vcc
	s_cbranch_execz .LBB0_85
	v_fma_f32 v114, s0, v25, v1
	v_mul_f32_e32 v115, 0x4b800000, v114
	v_cmp_gt_f32_e64 s[0:1], s7, v114
	s_add_u32 s18, s72, s8
	s_addc_u32 s19, s73, s9
	v_cndmask_b32_e64 v114, v114, v115, s[0:1]
	v_rsq_f32_e32 v114, v114
	s_nop 0
	v_mul_f32_e32 v115, 0x45800000, v114
	v_cndmask_b32_e64 v114, v114, v115, s[0:1]
	global_store_dword v24, v114, s[18:19] offset:4
	s_branch .LBB0_85
